# weight transposes (except layer-0 w_in) moved out of phase 0 into the idle tail of the in-projection GEMM (2-tile workgroups run them while others do their 3rd tile)
# speedup vs baseline: 1.0615x; 1.0047x over previous
.LBB0_19:
	v_readlane_b32 s62, v253, 4
	v_readlane_b32 s64, v253, 9
	s_lshl_b32 s69, s62, 3
	v_readlane_b32 s66, v253, 11
	s_add_i32 s22, s16, s69
	s_lshl_b32 s70, s66, 3
	v_readlane_b32 s60, v253, 13
	v_readlane_b32 s65, v253, 10
	v_readlane_b32 s67, v253, 12
	s_mov_b32 s100, 0
	s_movk_i32 s101, 0x2ff
	s_cmp_gt_i32 s22, s101
	v_readlane_b32 s61, v253, 14
	v_readlane_b32 s63, v253, 8
	v_readlane_b32 s68, v253, 7
	v_readlane_b32 s37, v253, 5
	s_barrier
	s_cbranch_scc1 .LBB0_50
.Ltr_entry:
	v_lshrrev_b32_e32 v8, 5, v24
	s_movk_i32 s2, 0x84
	v_mov_b32_e32 v4, 0x630
	v_mad_u32_u24 v7, v8, s2, v4
	v_mov_b32_e32 v4, 0xc60
	s_lshl_b32 s0, s16, 14
	v_mad_u32_u24 v48, v8, s2, v4
	v_mov_b32_e32 v4, 0x1290
	s_add_i32 s0, s0, 0
	v_and_b32_e32 v2, 31, v25
	v_mad_u32_u24 v49, v8, s2, v4
	v_lshlrev_b32_e32 v4, 3, v24
	v_lshl_add_u32 v5, v2, 2, s0
	v_mul_u32_u24_e32 v6, 0x84, v8
	v_lshrrev_b32_e32 v42, 3, v24
	v_and_b32_e32 v4, 56, v4
	v_mul_u32_u24_e32 v24, 0x84, v4
	v_lshlrev_b32_e32 v43, 2, v42
	s_add_u32 s23, s4, 0x200000
	v_add_u32_e32 v46, v5, v6
	v_add_u32_e32 v47, v5, v7
	v_add_u32_e32 v48, v5, v48
	v_add_u32_e32 v49, v5, v49
	s_mov_b32 s1, 0
	v_mov_b32_e32 v3, 0
	v_or_b32_e32 v9, 2, v8
	v_or_b32_e32 v10, 4, v8
	v_or_b32_e32 v11, 6, v8
	v_or_b32_e32 v12, 8, v8
	v_or_b32_e32 v13, 10, v8
	v_or_b32_e32 v14, 12, v8
	v_or_b32_e32 v15, 14, v8
	v_or_b32_e32 v16, 16, v8
	v_or_b32_e32 v17, 18, v8
	v_or_b32_e32 v18, 20, v8
	v_or_b32_e32 v19, 22, v8
	v_or_b32_e32 v20, 24, v8
	v_or_b32_e32 v21, 26, v8
	v_or_b32_e32 v23, 28, v8
	v_or_b32_e32 v25, 30, v8
	v_or_b32_e32 v26, 32, v8
	v_or_b32_e32 v27, 34, v8
	v_or_b32_e32 v28, 36, v8
	v_or_b32_e32 v29, 38, v8
	v_or_b32_e32 v30, 40, v8
	v_or_b32_e32 v31, 42, v8
	v_or_b32_e32 v32, 44, v8
	v_or_b32_e32 v33, 46, v8
	v_or_b32_e32 v34, 48, v8
	v_or_b32_e32 v35, 50, v8
	v_or_b32_e32 v36, 52, v8
	v_or_b32_e32 v37, 54, v8
	v_or_b32_e32 v38, 56, v8
	v_or_b32_e32 v39, 58, v8
	v_or_b32_e32 v40, 60, v8
	v_or_b32_e32 v41, 62, v8
	v_add3_u32 v24, s0, v24, v43
	v_or_b32_e32 v43, 8, v42
	v_or_b32_e32 v44, 16, v42
	v_or_b32_e32 v45, 24, v42
	s_addc_u32 s24, s5, 0
	s_lshl_b32 s25, s22, 1
	s_lshl_b32 s26, s70, 1
	s_lshl_b32 s27, s22, 6
	s_lshl_b32 s28, s70, 6
	s_mov_b64 s[10:11], 0x1400000
	s_movk_i32 s29, 0x7fff
	s_mov_b32 s30, 0xffff0000
	s_mov_b64 s[12:13], 0x900000
	s_mov_b64 s[14:15], 0x700000
	v_lshlrev_b32_e32 v2, 2, v2
	v_add_u32_e32 v50, 0x400, v46
	v_add_u32_e32 v51, 0x400, v47
	v_add_u32_e32 v52, 0x400, v48
	v_add_u32_e32 v53, 0x400, v49
	v_add_u32_e32 v54, 0x800, v49
	v_add_u32_e32 v55, 0xc00, v49
	v_lshlrev_b32_e32 v4, 1, v4
	s_branch .LBB0_23

.LBB0_22:
	s_add_i32 s22, s22, s70
	s_add_i32 s25, s25, s26
	s_add_i32 s27, s27, s28
	s_cmp_gt_i32 s22, s101
	s_cbranch_scc1 .LBB0_50

.LBB0_50:
	s_cmp_lg_u32 s100, 0
	s_cbranch_scc1 .Ltr_ret
	s_lshl_b32 s0, s66, 9
	s_cmpk_eq_i32 s66, 0x100
	s_cselect_b64 s[2:3], -1, 0
	s_cmpk_lg_i32 s66, 0x100
	s_cselect_b64 s[10:11], -1, 0
	v_lshl_add_u32 v2, s62, 9, v22
	v_writelane_b32 v253, s10, 15
	v_add_u32_e32 v3, 0xfffe8000, v2
	s_mov_b32 s1, 0x8000
	v_writelane_b32 v253, s11, 16
	v_writelane_b32 v253, s2, 17
	s_nop 1
	v_cndmask_b32_e64 v3, v2, v3, s[2:3]
	v_writelane_b32 v253, s3, 18
	v_cmp_gt_u32_e32 vcc, s1, v3
	s_and_saveexec_b64 s[10:11], vcc
	s_cbranch_execz .LBB0_55
	v_readlane_b32 s2, v253, 17
	v_readlane_b32 s3, v253, 18
	s_and_b64 s[2:3], s[2:3], exec
	s_load_dwordx2 s[2:3], s[8:9], 0x60
	v_and_b32_e32 v4, 63, v3
	s_cselect_b32 s1, 0x8000, s0
	s_add_u32 s12, s6, 0x140000
	v_lshlrev_b32_e32 v4, 2, v4
	v_mov_b32_e32 v5, 0
	s_addc_u32 s13, s7, 0
	s_waitcnt lgkmcnt(0)
	v_lshl_add_u64 v[6:7], s[2:3], 0, v[4:5]
	s_mov_b64 s[14:15], 0
	s_mov_b32 s18, 0xe000
	s_movk_i32 s19, 0x7fff

.LBB0_271:
	s_cmp_lt_u32 s62, 0x94
	s_cbranch_scc1 .Ltr_skip
	v_writelane_b32 v130, s8, 0
	v_writelane_b32 v130, s9, 1
	v_writelane_b32 v130, s10, 2
	v_writelane_b32 v130, s11, 3
	v_writelane_b32 v130, s12, 4
	v_writelane_b32 v130, s13, 5
	v_writelane_b32 v130, s14, 6
	v_writelane_b32 v130, s15, 7
	v_writelane_b32 v130, s16, 8
	v_writelane_b32 v130, s17, 9
	v_writelane_b32 v130, s22, 10
	v_writelane_b32 v130, s33, 11
	v_writelane_b32 v130, s70, 12
	v_mov_b32_e32 v131, v79
	v_mov_b32_e32 v132, v103
	v_readlane_b32 s0, v254, 47
	s_waitcnt vmcnt(0) lgkmcnt(0)
	s_barrier
	s_mov_b64 s[8:9], s[60:61]
	s_load_dwordx2 s[4:5], s[8:9], 0xc0
	s_lshr_b32 s16, s68, 6
	v_mbcnt_lo_u32_b32 v25, -1, 0
	v_mbcnt_hi_u32_b32 v25, -1, v25
	v_and_b32_e32 v24, 63, v25
	s_sub_i32 s1, s62, 0x94
	s_lshl_b32 s1, s1, 3
	s_add_i32 s1, s1, s16
	s_movk_i32 s22, 0x1880
	s_movk_i32 s101, 0x2aff
	s_cmp_eq_u32 s0, 0
	s_cbranch_scc0 .Ltr_l1
	s_movk_i32 s22, 0x300
	s_movk_i32 s101, 0x187f
.Ltr_l1:
	s_add_i32 s22, s22, s1
	s_movk_i32 s70, 0x360
	s_mov_b32 s100, 1
	s_waitcnt lgkmcnt(0)
	s_cmp_gt_i32 s22, s101
	s_cbranch_scc1 .Ltr_ret
	s_branch .Ltr_entry
.Ltr_ret:
	s_nop 0
	v_readlane_b32 s8, v130, 0
	v_readlane_b32 s9, v130, 1
	v_readlane_b32 s10, v130, 2
	v_readlane_b32 s11, v130, 3
	v_readlane_b32 s12, v130, 4
	v_readlane_b32 s13, v130, 5
	v_readlane_b32 s14, v130, 6
	v_readlane_b32 s15, v130, 7
	v_readlane_b32 s16, v130, 8
	v_readlane_b32 s17, v130, 9
	v_readlane_b32 s22, v130, 10
	v_readlane_b32 s33, v130, 11
	v_readlane_b32 s70, v130, 12
	v_mov_b32_e32 v79, v131
	v_mov_b32_e32 v103, v132
	s_mov_b32 s100, 0
	s_nop 4

	.amdhsa_kernel _Z14fwd_megakernel6Params
		.amdhsa_group_segment_fixed_size 0
		.amdhsa_private_segment_fixed_size 0
		.amdhsa_kernarg_size 456
		.amdhsa_user_sgpr_count 2
		.amdhsa_user_sgpr_dispatch_ptr 0
		.amdhsa_user_sgpr_queue_ptr 0
		.amdhsa_user_sgpr_kernarg_segment_ptr 1
		.amdhsa_user_sgpr_dispatch_id 0
		.amdhsa_user_sgpr_kernarg_preload_length 0
		.amdhsa_user_sgpr_kernarg_preload_offset 0
		.amdhsa_user_sgpr_private_segment_size 0
		.amdhsa_uses_dynamic_stack 0
		.amdhsa_enable_private_segment 0
		.amdhsa_system_sgpr_workgroup_id_x 1
		.amdhsa_system_sgpr_workgroup_id_y 0
		.amdhsa_system_sgpr_workgroup_id_z 0
		.amdhsa_system_sgpr_workgroup_info 0
		.amdhsa_system_vgpr_workitem_id 2
		.amdhsa_next_free_vgpr 256
		.amdhsa_next_free_sgpr 102
		.amdhsa_accum_offset 256
		.amdhsa_reserve_vcc 1
		.amdhsa_float_round_mode_32 0
		.amdhsa_float_round_mode_16_64 0
		.amdhsa_float_denorm_mode_32 3
		.amdhsa_float_denorm_mode_16_64 3
		.amdhsa_dx10_clamp 1
		.amdhsa_ieee_mode 1
		.amdhsa_fp16_overflow 0
		.amdhsa_tg_split 0
		.amdhsa_exception_fp_ieee_invalid_op 0
		.amdhsa_exception_fp_denorm_src 0
		.amdhsa_exception_fp_ieee_div_zero 0
		.amdhsa_exception_fp_ieee_overflow 0
		.amdhsa_exception_fp_ieee_underflow 0
		.amdhsa_exception_fp_ieee_inexact 0
		.amdhsa_exception_int_div_zero 0
	.end_amdhsa_kernel

amdhsa.kernels:
  - .agpr_count:     0
    .args:
      - .offset:         0
        .size:           200
        .value_kind:     by_value
      - .offset:         200
        .size:           4
        .value_kind:     hidden_block_count_x
      - .offset:         204
        .size:           4
        .value_kind:     hidden_block_count_y
      - .offset:         208
        .size:           4
        .value_kind:     hidden_block_count_z
      - .offset:         212
        .size:           2
        .value_kind:     hidden_group_size_x
      - .offset:         214
        .size:           2
        .value_kind:     hidden_group_size_y
      - .offset:         216
        .size:           2
        .value_kind:     hidden_group_size_z
      - .offset:         218
        .size:           2
        .value_kind:     hidden_remainder_x
      - .offset:         220
        .size:           2
        .value_kind:     hidden_remainder_y
      - .offset:         222
        .size:           2
        .value_kind:     hidden_remainder_z
      - .offset:         240
        .size:           8
        .value_kind:     hidden_global_offset_x
      - .offset:         248
        .size:           8
        .value_kind:     hidden_global_offset_y
      - .offset:         256
        .size:           8
        .value_kind:     hidden_global_offset_z
      - .offset:         264
        .size:           2
        .value_kind:     hidden_grid_dims
      - .offset:         288
        .size:           8
        .value_kind:     hidden_multigrid_sync_arg
      - .offset:         320
        .size:           4
        .value_kind:     hidden_dynamic_lds_size
    .group_segment_fixed_size: 0
    .kernarg_segment_align: 8
    .kernarg_segment_size: 456
    .language:       OpenCL C
    .language_version:
      - 2
      - 0
    .max_flat_workgroup_size: 512
    .name:           _Z14fwd_megakernel6Params
    .private_segment_fixed_size: 0
    .sgpr_count:     108
    .sgpr_spill_count: 194
    .symbol:         _Z14fwd_megakernel6Params.kd
    .uniform_work_group_size: 1
    .uses_dynamic_stack: false
    .vgpr_count:     256
    .vgpr_spill_count: 0
    .wavefront_size: 64
